# diff unit prologue: the bias-table load no longer waits vmcnt(0) right after issue; the wait (counted, vmcnt(8)) and the scale moved to its first consumer after the batched tile loads
# speedup vs baseline: 1.0001x; 1.0001x over previous
.LBB0_464:
	s_or_b64 exec, exec, s[4:5]
	s_load_dwordx2 s[4:5], s[66:67], 0x50
	v_lshl_or_b32 v2, v0, 2, s7
	v_ashrrev_i32_e32 v3, 31, v2
	s_waitcnt lgkmcnt(0)
	v_lshl_add_u64 v[2:3], v[2:3], 2, s[4:5]
	global_load_dword v41, v[2:3], off

.LBB0_467:
	s_or_b64 exec, exec, s[2:3]
	s_and_b64 s[0:1], s[0:1], exec
	s_cselect_b32 s2, s8, s6
	v_ashrrev_i32_e32 v147, 7, v134
	s_lshl_b32 s0, s2, 7
	v_ashrrev_i32_e32 v37, 4, v134
	v_and_b32_e32 v68, 31, v134
	v_lshl_add_u32 v69, v147, 5, s0
	v_add_u32_e32 v70, s9, v37
	v_mov_b64_e32 v[2:3], s[30:31]
	s_movk_i32 s3, 0x1c00
	v_or_b32_e32 v148, v69, v68
	v_and_b32_e32 v38, 15, v134
	v_mad_i64_i32 v[4:5], s[0:1], v70, s3, v[2:3]
	s_mov_b32 s49, s53
	v_ashrrev_i32_e32 v36, 3, v134
	v_lshl_add_u64 v[4:5], v[4:5], 0, s[48:49]
	v_lshlrev_b32_e32 v0, 4, v38
	v_add_u32_e32 v132, s9, v148
	v_bfe_u32 v146, v134, 6, 1
	v_lshl_add_u64 v[66:67], v[4:5], 0, v[0:1]
	v_add_u32_e32 v4, s10, v36
	v_mad_i64_i32 v[2:3], s[0:1], v132, s3, v[2:3]
	v_bfe_u32 v135, v134, 5, 1
	v_ashrrev_i32_e32 v5, 31, v4
	v_lshl_add_u64 v[2:3], v[2:3], 0, s[48:49]
	v_lshlrev_b32_e32 v136, 7, v146
	v_mov_b32_e32 v137, v1
	v_and_b32_e32 v6, 7, v134
	v_lshlrev_b64 v[4:5], 15, v[4:5]
	v_lshl_add_u64 v[2:3], v[2:3], 0, v[136:137]
	v_lshlrev_b32_e32 v130, 4, v135
	v_mov_b32_e32 v131, v1
	v_lshl_add_u64 v[4:5], s[36:37], 0, v[4:5]
	v_lshlrev_b32_e32 v34, 4, v6
	v_mov_b32_e32 v35, v1
	v_lshl_add_u64 v[2:3], v[2:3], 0, v[130:131]
	s_mov_b64 s[0:1], 0x1400
	v_lshl_add_u64 v[138:139], v[4:5], 0, v[34:35]
	v_lshl_add_u64 v[4:5], v[2:3], 0, s[0:1]
	s_movk_i32 s0, 0x1000
	v_add_co_u32_e32 v2, vcc, s0, v2
	global_load_dwordx4 v[22:25], v[4:5], off offset:64
	global_load_dwordx4 v[14:17], v[4:5], off offset:96
	v_addc_co_u32_e32 v3, vcc, 0, v3, vcc
	v_add_co_u32_e32 v6, vcc, s0, v66
	s_movk_i32 s0, 0xc1
	s_nop 0
	v_addc_co_u32_e32 v7, vcc, 0, v67, vcc
	v_add_co_u32_e32 v10, vcc, 0x39000, v66
	global_load_dwordx4 v[30:33], v[2:3], off offset:1024
	s_nop 0
	global_load_dwordx4 v[6:9], v[6:7], off offset:2048
	v_addc_co_u32_e32 v11, vcc, 0, v67, vcc
	v_add_co_u32_e32 v12, vcc, 0x200000, v138
	global_load_dwordx4 v[26:29], v[4:5], off offset:32
	s_nop 0
	global_load_dwordx4 v[2:5], v[138:139], off
	v_addc_co_u32_e32 v13, vcc, 0, v139, vcc
	global_load_dwordx4 v[18:21], v[10:11], off offset:2048
	s_nop 0
	global_load_dwordx4 v[10:13], v[12:13], off
	v_cmp_gt_i32_e32 vcc, s0, v134
	s_barrier
	s_and_saveexec_b64 s[0:1], vcc
	s_cbranch_execz .LBB0_469
	v_lshl_add_u32 v35, v134, 2, 0
	v_cmp_lt_i32_e32 vcc, 63, v134
	v_mov_b32_e32 v44, 0xff800000
	v_add_u32_e32 v35, 0x11800, v35
	s_waitcnt vmcnt(8)
	v_mul_f32_e32 v41, 0x3fb8aa3b, v41
	v_cndmask_b32_e32 v41, v44, v41, vcc
	ds_write_b32 v35, v41
